# in-proj GEMMs: row sums staged to LDS in the peeled first K iteration as in swiglu (epilogue reads LDS, no vmcnt(0) drain)
# speedup vs baseline: 1.0182x; 1.0009x over previous
; DEVI size_t gemm_offB(const Gemm& g, const Unit& u) { return (g.split ? (size_t)(u.b >> 2) * g.sB + (size_t)(u.b & 3) * g.sB_lo : (size_t)u.b * g.sB) + (size_t)(u.pm >> g.pmsh) * g.sBpm; }
; #define PG8_STAGE(bufoff, gbase, voff) do { _Pragma("unroll") for (int _i = 0; _i < 2; ++_i) \
;         __builtin_amdgcn_global_load_lds((const unsigned*)((const char*)(gbase) + (voff)[_i]), (LAS unsigned*)(lds + (bufoff) + ldsw + _i * 8192), 16, 0, 0); } while (0)
; #define PG8_LDA(dst, b, h) do { _Pragma("unroll") for (int m = 0; m < 4; ++m) _Pragma("unroll") for (int k = 0; k < 2; ++k) dst[m][k] = *(const LAS bf16x8*)(lds + PG8_SA(b, h) + aoff + m * 2048 + k * 1024); } while (0)
; #define PG8_LDB(dst, b, h) do { _Pragma("unroll") for (int n = 0; n < 2; ++n) _Pragma("unroll") for (int k = 0; k < 2; ++k) dst[n][k] = *(const LAS bf16x8*)(lds + PG8_SB(b, h) + boff + n * 2048 + k * 1024); } while (0)
; #define PG8_WAIT_L(n) asm volatile("s_waitcnt lgkmcnt(" #n ")" ::: "memory")
; #define PG8_BAR __builtin_amdgcn_s_barrier()
; template <class Epi>
; DEVI void gemm_phase(LAS unsigned char* lds, const Gemm g, const Epi& E) {
;     ...
;         const bool has_next = unit_next(g, ui + 1, nxt);
;         const char* nA = has_next ? (const char*)g.A + gemm_offA(g, nxt) * 2 + (size_t)nxt.pm * tstepA : cA;
;         const char* nB = has_next ? (const char*)g.Bt + gemm_offB(g, nxt) * 2 + (size_t)nxt.pn * tstepB : cB;
;         for (int t = 0; t < nt; t += 2) {
;             const bool last = (t == nt - 2);
;             const char* a1 = cA + (size_t)(t + 1) * kstep;
;             const char* a2 = last ? nA : cA + (size_t)(t + 2) * kstep; const char* b2 = last ? nB : cB + (size_t)(t + 2) * kstep;
;             const char* a3 = a2 + kstep; const char* b3 = b2 + kstep;
;             PG8_LDB(B0, 0, 0); PG8_SCHED; PG8_LDA(At, 0, 0); PG8_STAGE(PG8_SA(1, 1), a1 + hstepA, voffA);
;             PG8_WAIT_L(8); PG8_BAR; PG8_WAIT_L(0); PG8_MMA(0, 0, At, B0); PG8_BAR; PG8_SCHED;
;             PG8_LDB(B1, 0, 1); PG8_STAGE(PG8_SB(0, 0), b2, voffB);
;             PG8_BAR; PG8_WAIT_L(0); PG8_MMA(0, 1, At, B1); PG8_BAR;
;             PG8_LDA(At, 0, 1); PG8_STAGE(PG8_SA(0, 0), a2, voffA);
;             PG8_BAR; PG8_WAIT_L(0); PG8_MMA(1, 0, At, B0); PG8_BAR; PG8_SCHED;
;     ...
;                 for (int i = 0; i < 8; ++i) q4[i] = *(const f32x4*)(E.ssq_in + (size_t)(row0 + (i >> 2) * HALF + (i & 3) * 16) * 4);
.LBB0_275:
	s_ashr_i32 s13, s12, 31
	v_mov_b64_e32 v[0:1], 0x680
	s_lshl_b64 s[0:1], s[12:13], 19
	v_cmp_lt_i64_e32 vcc, s[16:17], v[0:1]
	s_add_u32 s16, s24, s0
	s_addc_u32 s17, s25, s1
	s_and_b64 s[0:1], vcc, exec
	s_cselect_b32 s0, s17, s9
	s_cselect_b32 s1, s16, s8
	s_ashr_i32 s15, s14, 31
	s_lshl_b64 s[18:19], s[14:15], 19
	s_add_u32 s36, s40, s18
	s_addc_u32 s37, s41, s19
	s_and_b64 s[18:19], vcc, exec
	s_cselect_b32 s5, s37, s47
	s_cselect_b32 s7, s36, s46
	s_add_u32 s8, s8, 0x40080
	s_addc_u32 s9, s9, 0
	s_add_u32 s13, s46, 0x100
	s_addc_u32 s15, s47, 0
	s_mov_b32 s18, -2
	s_cmp_eq_u32 s4, 12
	s_cbranch_scc1 .Lip13l_a_in
	v_and_b32_e32 v248, 0xff, v154
	v_lshlrev_b32_e32 v248, 4, v248
	v_add_u32_e32 v249, 0x21000, v248
	v_lshl_add_u32 v248, s6, 12, v248
	global_load_dwordx4 v[244:247], v248, s[76:77]
	s_add_u32 s19, s8, 0xfffc0080
	s_addc_u32 s26, s9, -1
	s_add_i32 s27, 0, 0x10000
	v_add_u32_e32 v8, s27, v214
	ds_read_b128 v[130:133], v8
	ds_read_b128 v[134:137], v8 offset:1024
	ds_read_b128 v[138:141], v8 offset:2048
	ds_read_b128 v[142:145], v8 offset:3072
	s_cmp_eq_u32 s18, 12
	s_cselect_b32 s69, s0, s26
	s_cselect_b32 s68, s1, s19
	s_cselect_b32 s47, s5, s15
	s_cselect_b32 s46, s7, s13
	v_lshl_add_u64 v[208:209], s[8:9], 0, v[184:185]
	s_add_i32 m0, s81, 0xc000
	ds_read_b128 v[146:149], v216
	ds_read_b128 v[150:153], v216 offset:1024
	ds_read_b128 v[188:191], v216 offset:2048
	ds_read_b128 v[192:195], v216 offset:3072
	ds_read_b128 v[196:199], v216 offset:4096
	ds_read_b128 v[200:203], v216 offset:5120
	ds_read_b128 v[204:207], v216 offset:6144
	ds_read_b128 v[218:221], v216 offset:7168
	global_load_lds_dwordx4 v[208:209], off
	s_add_i32 m0, s81, 0xe000
	v_lshl_add_u64 v[208:209], s[8:9], 0, v[186:187]
	global_load_lds_dwordx4 v[208:209], off
	s_waitcnt lgkmcnt(8)
	s_barrier
	s_waitcnt lgkmcnt(0)
	v_mfma_f32_16x16x32_bf16 v[126:129], v[130:133], v[146:149], 0
	v_mfma_f32_16x16x32_bf16 v[122:125], v[138:141], v[146:149], 0
	v_mfma_f32_16x16x32_bf16 v[114:117], v[130:133], v[188:191], 0
	v_mfma_f32_16x16x32_bf16 v[106:109], v[138:141], v[188:191], 0
	v_mfma_f32_16x16x32_bf16 v[94:97], v[130:133], v[196:199], 0
	v_mfma_f32_16x16x32_bf16 v[90:93], v[138:141], v[196:199], 0
	v_mfma_f32_16x16x32_bf16 v[82:85], v[130:133], v[204:207], 0
	v_mfma_f32_16x16x32_bf16 v[74:77], v[138:141], v[204:207], 0
	v_mfma_f32_16x16x32_bf16 v[126:129], v[134:137], v[150:153], v[126:129]
	v_mfma_f32_16x16x32_bf16 v[122:125], v[142:145], v[150:153], v[122:125]
	v_mfma_f32_16x16x32_bf16 v[114:117], v[134:137], v[192:195], v[114:117]
	v_mfma_f32_16x16x32_bf16 v[106:109], v[142:145], v[192:195], v[106:109]
	v_mfma_f32_16x16x32_bf16 v[94:97], v[134:137], v[200:203], v[94:97]
	v_mfma_f32_16x16x32_bf16 v[90:93], v[142:145], v[200:203], v[90:93]
	v_mfma_f32_16x16x32_bf16 v[82:85], v[134:137], v[218:221], v[82:85]
	v_mfma_f32_16x16x32_bf16 v[74:77], v[142:145], v[218:221], v[74:77]
	s_barrier
	s_add_i32 s19, 0, 0x14000
	s_add_i32 s26, s27, s80
	v_add_u32_e32 v8, s19, v214
	v_lshl_add_u64 v[208:209], s[46:47], 0, v[178:179]
	s_mov_b32 m0, s26
	ds_read_b128 v[222:225], v8
	ds_read_b128 v[226:229], v8 offset:1024
	ds_read_b128 v[230:233], v8 offset:2048
	ds_read_b128 v[234:237], v8 offset:3072
	global_load_lds_dwordx4 v[208:209], off
	s_add_i32 m0, s26, 0x2000
	v_lshl_add_u64 v[238:239], s[46:47], 0, v[182:183]
	global_load_lds_dwordx4 v[238:239], off
	s_barrier
	s_waitcnt lgkmcnt(0)
	v_mfma_f32_16x16x32_bf16 v[118:121], v[222:225], v[146:149], 0
	v_mfma_f32_16x16x32_bf16 v[110:113], v[230:233], v[146:149], 0
	v_mfma_f32_16x16x32_bf16 v[102:105], v[222:225], v[188:191], 0
	v_mfma_f32_16x16x32_bf16 v[98:101], v[230:233], v[188:191], 0
	v_mfma_f32_16x16x32_bf16 v[86:89], v[222:225], v[196:199], 0
	v_mfma_f32_16x16x32_bf16 v[78:81], v[230:233], v[196:199], 0
	v_mfma_f32_16x16x32_bf16 v[62:65], v[222:225], v[204:207], 0
	v_mfma_f32_16x16x32_bf16 v[58:61], v[230:233], v[204:207], 0
	v_mfma_f32_16x16x32_bf16 v[118:121], v[226:229], v[150:153], v[118:121]
	v_mfma_f32_16x16x32_bf16 v[110:113], v[234:237], v[150:153], v[110:113]
	v_mfma_f32_16x16x32_bf16 v[102:105], v[226:229], v[192:195], v[102:105]
	v_mfma_f32_16x16x32_bf16 v[98:101], v[234:237], v[192:195], v[98:101]
	v_mfma_f32_16x16x32_bf16 v[86:89], v[226:229], v[200:203], v[86:89]
	v_mfma_f32_16x16x32_bf16 v[78:81], v[234:237], v[200:203], v[78:81]
	v_mfma_f32_16x16x32_bf16 v[62:65], v[226:229], v[218:221], v[62:65]
	v_mfma_f32_16x16x32_bf16 v[58:61], v[234:237], v[218:221], v[58:61]
	s_mov_b32 m0, s81
	v_lshl_add_u64 v[240:241], s[68:69], 0, v[176:177]
	s_barrier
	ds_read_b128 v[146:149], v216 offset:16384
	ds_read_b128 v[150:153], v216 offset:17408
	ds_read_b128 v[188:191], v216 offset:18432
	ds_read_b128 v[192:195], v216 offset:19456
	ds_read_b128 v[196:199], v216 offset:20480
	ds_read_b128 v[200:203], v216 offset:21504
	ds_read_b128 v[204:207], v216 offset:22528
	ds_read_b128 v[218:221], v216 offset:23552
	global_load_lds_dwordx4 v[240:241], off
	s_mov_b32 m0, s82
	v_lshl_add_u64 v[242:243], s[68:69], 0, v[180:181]
	global_load_lds_dwordx4 v[242:243], off
	s_barrier
	s_waitcnt lgkmcnt(0)
	v_mfma_f32_16x16x32_bf16 v[70:73], v[130:133], v[146:149], 0
	v_mfma_f32_16x16x32_bf16 v[66:69], v[138:141], v[146:149], 0
	v_mfma_f32_16x16x32_bf16 v[46:49], v[130:133], v[188:191], 0
	v_mfma_f32_16x16x32_bf16 v[42:45], v[138:141], v[188:191], 0
	v_mfma_f32_16x16x32_bf16 v[30:33], v[130:133], v[196:199], 0
	v_mfma_f32_16x16x32_bf16 v[26:29], v[138:141], v[196:199], 0
	v_mfma_f32_16x16x32_bf16 v[14:17], v[130:133], v[204:207], 0
	v_mfma_f32_16x16x32_bf16 v[10:13], v[138:141], v[204:207], 0
	v_mfma_f32_16x16x32_bf16 v[70:73], v[134:137], v[150:153], v[70:73]
	v_mfma_f32_16x16x32_bf16 v[66:69], v[142:145], v[150:153], v[66:69]
	v_mfma_f32_16x16x32_bf16 v[46:49], v[134:137], v[192:195], v[46:49]
	v_mfma_f32_16x16x32_bf16 v[42:45], v[142:145], v[192:195], v[42:45]
	v_mfma_f32_16x16x32_bf16 v[30:33], v[134:137], v[200:203], v[30:33]
	v_mfma_f32_16x16x32_bf16 v[26:29], v[142:145], v[200:203], v[26:29]
	v_mfma_f32_16x16x32_bf16 v[14:17], v[134:137], v[218:221], v[14:17]
	v_mfma_f32_16x16x32_bf16 v[10:13], v[142:145], v[218:221], v[10:13]
	s_barrier
; #define PG8_STAGE(bufoff, gbase, voff) do { _Pragma("unroll") for (int _i = 0; _i < 2; ++_i) \
;         __builtin_amdgcn_global_load_lds((const unsigned*)((const char*)(gbase) + (voff)[_i]), (LAS unsigned*)(lds + (bufoff) + ldsw + _i * 8192), 16, 0, 0); } while (0)
; #define PG8_LDA(dst, b, h) do { _Pragma("unroll") for (int m = 0; m < 4; ++m) _Pragma("unroll") for (int k = 0; k < 2; ++k) dst[m][k] = *(const LAS bf16x8*)(lds + PG8_SA(b, h) + aoff + m * 2048 + k * 1024); } while (0)
; #define PG8_LDB(dst, b, h) do { _Pragma("unroll") for (int n = 0; n < 2; ++n) _Pragma("unroll") for (int k = 0; k < 2; ++k) dst[n][k] = *(const LAS bf16x8*)(lds + PG8_SB(b, h) + boff + n * 2048 + k * 1024); } while (0)
; #define PG8_MMA(ai, bj, At, Bt) do { __builtin_amdgcn_s_setprio(1); _Pragma("unroll") for (int m = 0; m < 4; ++m) _Pragma("unroll") for (int n = 0; n < 2; ++n) _Pragma("unroll") for (int k = 0; k < 2; ++k) \
;         acc[ai][bj][m][n] = __builtin_amdgcn_mfma_f32_16x16x32_bf16(Bt[n][k], At[m][k], acc[ai][bj][m][n], 0, 0, 0); __builtin_amdgcn_s_setprio(0); } while (0)
; #define PG8_WAIT_V(n) asm volatile("s_waitcnt vmcnt(" #n ")" ::: "memory")
; #define PG8_WAIT_L(n) asm volatile("s_waitcnt lgkmcnt(" #n ")" ::: "memory")
; #define PG8_BAR __builtin_amdgcn_s_barrier()
; #define PG8_SCHED __builtin_amdgcn_sched_barrier(0)
; template <class Epi>
; DEVI void gemm_phase(LAS unsigned char* lds, const Gemm g, const Epi& E) {
;     ...
;             PG8_BAR; PG8_WAIT_L(0); PG8_MMA(1, 0, At, B0); PG8_BAR; PG8_SCHED;
;             PG8_STAGE(PG8_SB(0, 1), b2 + hstepB, voffB);
;             PG8_WAIT_V(6); PG8_BAR; PG8_MMA(1, 1, At, B1); PG8_BAR;
;             PG8_LDB(B0, 1, 0); PG8_SCHED; PG8_LDA(At, 1, 0); PG8_STAGE(PG8_SA(0, 1), a2 + hstepA, voffA);
;             PG8_WAIT_L(8); PG8_BAR; PG8_WAIT_L(0); PG8_MMA(0, 0, At, B0); PG8_BAR; PG8_SCHED;
;             PG8_LDB(B1, 1, 1); PG8_STAGE(PG8_SB(1, 0), b3, voffB);
;             PG8_BAR; PG8_WAIT_L(0); PG8_MMA(0, 1, At, B1); PG8_BAR;
;             PG8_LDA(At, 1, 1); PG8_STAGE(PG8_SA(1, 0), a3, voffA);
;             PG8_BAR; PG8_WAIT_L(0); PG8_MMA(1, 0, At, B0); PG8_BAR; PG8_SCHED;
;             PG8_STAGE(PG8_SB(1, 1), b3 + hstepB, voffB);
;             PG8_WAIT_V(6); PG8_BAR; PG8_MMA(1, 1, At, B1); PG8_BAR;
	s_add_u32 s26, s46, 0x40000
	s_addc_u32 s27, s47, 0
	s_add_i32 s19, s19, s80
	s_mov_b32 m0, s19
	v_lshl_add_u64 v[130:131], s[26:27], 0, v[178:179]
	global_load_lds_dwordx4 v[130:131], off
	s_add_i32 m0, s19, 0x2000
	v_lshl_add_u64 v[130:131], s[26:27], 0, v[182:183]
	global_load_lds_dwordx4 v[130:131], off
	s_waitcnt vmcnt(6)
	ds_write_b128 v249, v[244:247]
	s_barrier
	v_mfma_f32_16x16x32_bf16 v[50:53], v[222:225], v[146:149], 0
	v_mfma_f32_16x16x32_bf16 v[54:57], v[230:233], v[146:149], 0
	v_mfma_f32_16x16x32_bf16 v[34:37], v[222:225], v[188:191], 0
	v_mfma_f32_16x16x32_bf16 v[38:41], v[230:233], v[188:191], 0
	v_mfma_f32_16x16x32_bf16 v[18:21], v[222:225], v[196:199], 0
	v_mfma_f32_16x16x32_bf16 v[22:25], v[230:233], v[196:199], 0
	v_mfma_f32_16x16x32_bf16 v[0:3], v[222:225], v[204:207], 0
	v_mfma_f32_16x16x32_bf16 v[4:7], v[230:233], v[204:207], 0
	v_mfma_f32_16x16x32_bf16 v[50:53], v[226:229], v[150:153], v[50:53]
	v_mfma_f32_16x16x32_bf16 v[54:57], v[234:237], v[150:153], v[54:57]
	v_mfma_f32_16x16x32_bf16 v[34:37], v[226:229], v[192:195], v[34:37]
	v_mfma_f32_16x16x32_bf16 v[38:41], v[234:237], v[192:195], v[38:41]
	v_mfma_f32_16x16x32_bf16 v[18:21], v[226:229], v[200:203], v[18:21]
	v_mfma_f32_16x16x32_bf16 v[22:25], v[234:237], v[200:203], v[22:25]
	v_mfma_f32_16x16x32_bf16 v[0:3], v[226:229], v[218:221], v[0:3]
	v_mfma_f32_16x16x32_bf16 v[4:7], v[234:237], v[218:221], v[4:7]
	s_add_i32 s19, 0, 0x18000
	v_add_u32_e32 v8, s19, v214
	s_barrier
	ds_read_b128 v[130:133], v8
	ds_read_b128 v[134:137], v8 offset:1024
	ds_read_b128 v[138:141], v8 offset:2048
	ds_read_b128 v[142:145], v8 offset:3072
	s_add_u32 s26, s68, 0x40000
	s_addc_u32 s27, s69, 0
	s_mov_b32 m0, s83
	v_lshl_add_u64 v[222:223], s[26:27], 0, v[176:177]
	ds_read_b128 v[146:149], v216 offset:32768
	ds_read_b128 v[150:153], v216 offset:33792
	ds_read_b128 v[188:191], v216 offset:34816
	ds_read_b128 v[192:195], v216 offset:35840
	ds_read_b128 v[196:199], v216 offset:36864
	ds_read_b128 v[200:203], v216 offset:37888
	ds_read_b128 v[204:207], v216 offset:38912
	ds_read_b128 v[218:221], v216 offset:39936
	global_load_lds_dwordx4 v[222:223], off
	s_mov_b32 m0, s84
	v_lshl_add_u64 v[222:223], s[26:27], 0, v[180:181]
	global_load_lds_dwordx4 v[222:223], off
	s_waitcnt lgkmcnt(8)
	s_barrier
	s_waitcnt lgkmcnt(0)
	v_mfma_f32_16x16x32_bf16 v[126:129], v[130:133], v[146:149], v[126:129]
	v_mfma_f32_16x16x32_bf16 v[122:125], v[138:141], v[146:149], v[122:125]
	v_mfma_f32_16x16x32_bf16 v[114:117], v[130:133], v[188:191], v[114:117]
	v_mfma_f32_16x16x32_bf16 v[106:109], v[138:141], v[188:191], v[106:109]
	v_mfma_f32_16x16x32_bf16 v[94:97], v[130:133], v[196:199], v[94:97]
	v_mfma_f32_16x16x32_bf16 v[90:93], v[138:141], v[196:199], v[90:93]
	v_mfma_f32_16x16x32_bf16 v[82:85], v[130:133], v[204:207], v[82:85]
	v_mfma_f32_16x16x32_bf16 v[74:77], v[138:141], v[204:207], v[74:77]
	v_mfma_f32_16x16x32_bf16 v[126:129], v[134:137], v[150:153], v[126:129]
	v_mfma_f32_16x16x32_bf16 v[122:125], v[142:145], v[150:153], v[122:125]
	v_mfma_f32_16x16x32_bf16 v[114:117], v[134:137], v[192:195], v[114:117]
	v_mfma_f32_16x16x32_bf16 v[106:109], v[142:145], v[192:195], v[106:109]
	v_mfma_f32_16x16x32_bf16 v[94:97], v[134:137], v[200:203], v[94:97]
	v_mfma_f32_16x16x32_bf16 v[90:93], v[142:145], v[200:203], v[90:93]
	v_mfma_f32_16x16x32_bf16 v[82:85], v[134:137], v[218:221], v[82:85]
	v_mfma_f32_16x16x32_bf16 v[74:77], v[142:145], v[218:221], v[74:77]
	s_barrier
	s_add_i32 s38, 0, 0x1c000
	s_add_i32 s19, s19, s80
	v_add_u32_e32 v8, s38, v214
	v_lshl_add_u64 v[208:209], v[208:209], 0, s[70:71]
	s_mov_b32 m0, s19
	ds_read_b128 v[222:225], v8
	ds_read_b128 v[226:229], v8 offset:1024
	ds_read_b128 v[230:233], v8 offset:2048
	ds_read_b128 v[234:237], v8 offset:3072
	global_load_lds_dwordx4 v[208:209], off
	s_add_i32 m0, s19, 0x2000
	v_lshl_add_u64 v[208:209], v[238:239], 0, s[70:71]
	global_load_lds_dwordx4 v[208:209], off
	s_barrier
; #define PG8_STAGE(bufoff, gbase, voff) do { _Pragma("unroll") for (int _i = 0; _i < 2; ++_i) \
;         __builtin_amdgcn_global_load_lds((const unsigned*)((const char*)(gbase) + (voff)[_i]), (LAS unsigned*)(lds + (bufoff) + ldsw + _i * 8192), 16, 0, 0); } while (0)
; #define PG8_LDA(dst, b, h) do { _Pragma("unroll") for (int m = 0; m < 4; ++m) _Pragma("unroll") for (int k = 0; k < 2; ++k) dst[m][k] = *(const LAS bf16x8*)(lds + PG8_SA(b, h) + aoff + m * 2048 + k * 1024); } while (0)
; #define PG8_LDB(dst, b, h) do { _Pragma("unroll") for (int n = 0; n < 2; ++n) _Pragma("unroll") for (int k = 0; k < 2; ++k) dst[n][k] = *(const LAS bf16x8*)(lds + PG8_SB(b, h) + boff + n * 2048 + k * 1024); } while (0)
; #define PG8_MMA(ai, bj, At, Bt) do { __builtin_amdgcn_s_setprio(1); _Pragma("unroll") for (int m = 0; m < 4; ++m) _Pragma("unroll") for (int n = 0; n < 2; ++n) _Pragma("unroll") for (int k = 0; k < 2; ++k) \
;         acc[ai][bj][m][n] = __builtin_amdgcn_mfma_f32_16x16x32_bf16(Bt[n][k], At[m][k], acc[ai][bj][m][n], 0, 0, 0); __builtin_amdgcn_s_setprio(0); } while (0)
; #define PG8_WAIT_V(n) asm volatile("s_waitcnt vmcnt(" #n ")" ::: "memory")
; #define PG8_WAIT_L(n) asm volatile("s_waitcnt lgkmcnt(" #n ")" ::: "memory")
; #define PG8_BAR __builtin_amdgcn_s_barrier()
; #define PG8_SCHED __builtin_amdgcn_sched_barrier(0)
; template <class Epi>
; DEVI void gemm_phase(LAS unsigned char* lds, const Gemm g, const Epi& E) {
;     ...
;             PG8_WAIT_V(6); PG8_BAR; PG8_MMA(1, 1, At, B1); PG8_BAR;
;             PG8_LDB(B0, 1, 0); PG8_SCHED; PG8_LDA(At, 1, 0); PG8_STAGE(PG8_SA(0, 1), a2 + hstepA, voffA);
;             PG8_WAIT_L(8); PG8_BAR; PG8_WAIT_L(0); PG8_MMA(0, 0, At, B0); PG8_BAR; PG8_SCHED;
;             PG8_LDB(B1, 1, 1); PG8_STAGE(PG8_SB(1, 0), b3, voffB);
;             PG8_BAR; PG8_WAIT_L(0); PG8_MMA(0, 1, At, B1); PG8_BAR;
;             PG8_LDA(At, 1, 1); PG8_STAGE(PG8_SA(1, 0), a3, voffA);
;             PG8_BAR; PG8_WAIT_L(0); PG8_MMA(1, 0, At, B0); PG8_BAR; PG8_SCHED;
;             PG8_STAGE(PG8_SB(1, 1), b3 + hstepB, voffB);
;             PG8_WAIT_V(6); PG8_BAR; PG8_MMA(1, 1, At, B1); PG8_BAR;
;         }
	s_waitcnt lgkmcnt(0)
	v_mfma_f32_16x16x32_bf16 v[118:121], v[222:225], v[146:149], v[118:121]
	v_mfma_f32_16x16x32_bf16 v[110:113], v[230:233], v[146:149], v[110:113]
	v_mfma_f32_16x16x32_bf16 v[102:105], v[222:225], v[188:191], v[102:105]
	v_mfma_f32_16x16x32_bf16 v[98:101], v[230:233], v[188:191], v[98:101]
	v_mfma_f32_16x16x32_bf16 v[86:89], v[222:225], v[196:199], v[86:89]
	v_mfma_f32_16x16x32_bf16 v[78:81], v[230:233], v[196:199], v[78:81]
	v_mfma_f32_16x16x32_bf16 v[62:65], v[222:225], v[204:207], v[62:65]
	v_mfma_f32_16x16x32_bf16 v[58:61], v[230:233], v[204:207], v[58:61]
	v_mfma_f32_16x16x32_bf16 v[118:121], v[226:229], v[150:153], v[118:121]
	v_mfma_f32_16x16x32_bf16 v[110:113], v[234:237], v[150:153], v[110:113]
	v_mfma_f32_16x16x32_bf16 v[102:105], v[226:229], v[192:195], v[102:105]
	v_mfma_f32_16x16x32_bf16 v[98:101], v[234:237], v[192:195], v[98:101]
	v_mfma_f32_16x16x32_bf16 v[86:89], v[226:229], v[200:203], v[86:89]
	v_mfma_f32_16x16x32_bf16 v[78:81], v[234:237], v[200:203], v[78:81]
	v_mfma_f32_16x16x32_bf16 v[62:65], v[226:229], v[218:221], v[62:65]
	v_mfma_f32_16x16x32_bf16 v[58:61], v[234:237], v[218:221], v[58:61]
	s_mov_b32 m0, s85
	v_lshl_add_u64 v[208:209], v[240:241], 0, s[70:71]
	s_barrier
	ds_read_b128 v[146:149], v216 offset:49152
	ds_read_b128 v[150:153], v216 offset:50176
	ds_read_b128 v[188:191], v216 offset:51200
	ds_read_b128 v[192:195], v216 offset:52224
	ds_read_b128 v[196:199], v216 offset:53248
	ds_read_b128 v[200:203], v216 offset:54272
	ds_read_b128 v[204:207], v216 offset:55296
	ds_read_b128 v[218:221], v216 offset:56320
	global_load_lds_dwordx4 v[208:209], off
	s_mov_b32 m0, s86
	v_lshl_add_u64 v[208:209], v[242:243], 0, s[70:71]
	global_load_lds_dwordx4 v[208:209], off
	s_barrier
	s_waitcnt lgkmcnt(0)
	v_mfma_f32_16x16x32_bf16 v[70:73], v[130:133], v[146:149], v[70:73]
	v_mfma_f32_16x16x32_bf16 v[66:69], v[138:141], v[146:149], v[66:69]
	v_mfma_f32_16x16x32_bf16 v[46:49], v[130:133], v[188:191], v[46:49]
	v_mfma_f32_16x16x32_bf16 v[42:45], v[138:141], v[188:191], v[42:45]
	v_mfma_f32_16x16x32_bf16 v[30:33], v[130:133], v[196:199], v[30:33]
	v_mfma_f32_16x16x32_bf16 v[26:29], v[138:141], v[196:199], v[26:29]
	v_mfma_f32_16x16x32_bf16 v[14:17], v[130:133], v[204:207], v[14:17]
	v_mfma_f32_16x16x32_bf16 v[10:13], v[138:141], v[204:207], v[10:13]
	v_mfma_f32_16x16x32_bf16 v[70:73], v[134:137], v[150:153], v[70:73]
	v_mfma_f32_16x16x32_bf16 v[66:69], v[142:145], v[150:153], v[66:69]
	v_mfma_f32_16x16x32_bf16 v[46:49], v[134:137], v[192:195], v[46:49]
	v_mfma_f32_16x16x32_bf16 v[42:45], v[142:145], v[192:195], v[42:45]
	v_mfma_f32_16x16x32_bf16 v[30:33], v[134:137], v[200:203], v[30:33]
	v_mfma_f32_16x16x32_bf16 v[26:29], v[142:145], v[200:203], v[26:29]
	v_mfma_f32_16x16x32_bf16 v[14:17], v[134:137], v[218:221], v[14:17]
	v_mfma_f32_16x16x32_bf16 v[10:13], v[142:145], v[218:221], v[10:13]
	s_barrier
	s_add_u32 s26, s46, 0x40080
	s_addc_u32 s27, s47, 0
	s_add_i32 s19, s38, s80
	s_mov_b32 m0, s19
	v_lshl_add_u64 v[130:131], s[26:27], 0, v[178:179]
	global_load_lds_dwordx4 v[130:131], off
	s_add_i32 m0, s19, 0x2000
	v_lshl_add_u64 v[130:131], s[26:27], 0, v[182:183]
	global_load_lds_dwordx4 v[130:131], off
	s_waitcnt vmcnt(6)
	s_barrier
	v_mfma_f32_16x16x32_bf16 v[50:53], v[222:225], v[146:149], v[50:53]
	v_mfma_f32_16x16x32_bf16 v[54:57], v[230:233], v[146:149], v[54:57]
	v_mfma_f32_16x16x32_bf16 v[34:37], v[222:225], v[188:191], v[34:37]
	v_mfma_f32_16x16x32_bf16 v[38:41], v[230:233], v[188:191], v[38:41]
	v_mfma_f32_16x16x32_bf16 v[18:21], v[222:225], v[196:199], v[18:21]
	v_mfma_f32_16x16x32_bf16 v[22:25], v[230:233], v[196:199], v[22:25]
	v_mfma_f32_16x16x32_bf16 v[0:3], v[222:225], v[204:207], v[0:3]
	v_mfma_f32_16x16x32_bf16 v[4:7], v[230:233], v[204:207], v[4:7]
	v_mfma_f32_16x16x32_bf16 v[50:53], v[226:229], v[150:153], v[50:53]
	v_mfma_f32_16x16x32_bf16 v[54:57], v[234:237], v[150:153], v[54:57]
	v_mfma_f32_16x16x32_bf16 v[34:37], v[226:229], v[192:195], v[34:37]
	v_mfma_f32_16x16x32_bf16 v[38:41], v[234:237], v[192:195], v[38:41]
	v_mfma_f32_16x16x32_bf16 v[18:21], v[226:229], v[200:203], v[18:21]
	v_mfma_f32_16x16x32_bf16 v[22:25], v[234:237], v[200:203], v[22:25]
	v_mfma_f32_16x16x32_bf16 v[0:3], v[226:229], v[218:221], v[0:3]
	v_mfma_f32_16x16x32_bf16 v[4:7], v[234:237], v[218:221], v[4:7]
	s_add_i32 s18, s18, 2
	s_add_u32 s8, s8, 0x100
	s_addc_u32 s9, s9, 0
	s_add_u32 s13, s13, 0x100
	s_addc_u32 s15, s15, 0
	s_cmp_gt_u32 s18, 13
	s_barrier

; #define PG8_STAGE(bufoff, gbase, voff) do { _Pragma("unroll") for (int _i = 0; _i < 2; ++_i) \
;         __builtin_amdgcn_global_load_lds((const unsigned*)((const char*)(gbase) + (voff)[_i]), (LAS unsigned*)(lds + (bufoff) + ldsw + _i * 8192), 16, 0, 0); } while (0)
; #define PG8_LDA(dst, b, h) do { _Pragma("unroll") for (int m = 0; m < 4; ++m) _Pragma("unroll") for (int k = 0; k < 2; ++k) dst[m][k] = *(const LAS bf16x8*)(lds + PG8_SA(b, h) + aoff + m * 2048 + k * 1024); } while (0)
; #define PG8_LDB(dst, b, h) do { _Pragma("unroll") for (int n = 0; n < 2; ++n) _Pragma("unroll") for (int k = 0; k < 2; ++k) dst[n][k] = *(const LAS bf16x8*)(lds + PG8_SB(b, h) + boff + n * 2048 + k * 1024); } while (0)
; #define PG8_MMA(ai, bj, At, Bt) do { __builtin_amdgcn_s_setprio(1); _Pragma("unroll") for (int m = 0; m < 4; ++m) _Pragma("unroll") for (int n = 0; n < 2; ++n) _Pragma("unroll") for (int k = 0; k < 2; ++k) \
;         acc[ai][bj][m][n] = __builtin_amdgcn_mfma_f32_16x16x32_bf16(Bt[n][k], At[m][k], acc[ai][bj][m][n], 0, 0, 0); __builtin_amdgcn_s_setprio(0); } while (0)
; #define PG8_WAIT_L(n) asm volatile("s_waitcnt lgkmcnt(" #n ")" ::: "memory")
; #define PG8_BAR __builtin_amdgcn_s_barrier()
; #define PG8_SCHED __builtin_amdgcn_sched_barrier(0)
; template <class Epi>
; DEVI void gemm_phase(LAS unsigned char* lds, const Gemm g, const Epi& E) {
;     ...
;             PG8_LDB(B0, 0, 0); PG8_SCHED; PG8_LDA(At, 0, 0); PG8_STAGE(PG8_SA(1, 1), a1 + hstepA, voffA);
;             PG8_WAIT_L(8); PG8_BAR; PG8_WAIT_L(0); PG8_MMA(0, 0, At, B0); PG8_BAR; PG8_SCHED;
;     ...
;                 for (int i = 0; i < 8; ++i) q4[i] = *(const f32x4*)(E.ssq_in + (size_t)(row0 + (i >> 2) * HALF + (i & 3) * 16) * 4);
.Lip13l_a_in:
	s_and_b32 s101, s66, 0xc0
	s_mov_b32 s100, 1
	s_cmp_lg_u32 s101, 0
	s_cselect_b32 s101, 1, 0
	v_and_b32_e32 v248, 0xff, v154
	v_lshlrev_b32_e32 v248, 4, v248
	v_add_u32_e32 v249, 0x21000, v248
	v_lshl_add_u32 v248, s6, 12, v248
	global_load_dwordx4 v[244:247], v248, s[76:77]
	s_add_u32 s19, s8, 0xfffc0080
	s_addc_u32 s26, s9, -1
	s_add_i32 s27, 0, 0x10000
	v_add_u32_e32 v8, s27, v214
	ds_read_b128 v[130:133], v8
	ds_read_b128 v[134:137], v8 offset:1024
	ds_read_b128 v[138:141], v8 offset:2048
	ds_read_b128 v[142:145], v8 offset:3072
	s_cmp_eq_u32 s18, 12
	s_cselect_b32 s69, s0, s26
	s_cselect_b32 s68, s1, s19
	s_cselect_b32 s47, s5, s15
	s_cselect_b32 s46, s7, s13
	v_lshl_add_u64 v[208:209], s[8:9], 0, v[184:185]
	s_add_i32 m0, s81, 0xc000
	ds_read_b128 v[146:149], v216
	ds_read_b128 v[150:153], v216 offset:1024
	ds_read_b128 v[188:191], v216 offset:2048
	ds_read_b128 v[192:195], v216 offset:3072
	ds_read_b128 v[196:199], v216 offset:4096
	ds_read_b128 v[200:203], v216 offset:5120
	ds_read_b128 v[204:207], v216 offset:6144
	ds_read_b128 v[218:221], v216 offset:7168
	global_load_lds_dwordx4 v[208:209], off
	s_add_i32 m0, s81, 0xe000
	v_lshl_add_u64 v[208:209], s[8:9], 0, v[186:187]
	global_load_lds_dwordx4 v[208:209], off
	s_waitcnt lgkmcnt(8)
	s_barrier
	s_waitcnt lgkmcnt(0)
	s_cmp_lg_u32 s101, 0
	s_cbranch_scc1 .Lip13l_a_0
	v_mfma_f32_16x16x32_bf16 v[126:129], v[130:133], v[146:149], 0
	v_mfma_f32_16x16x32_bf16 v[122:125], v[138:141], v[146:149], 0
	v_mfma_f32_16x16x32_bf16 v[114:117], v[130:133], v[188:191], 0
	v_mfma_f32_16x16x32_bf16 v[106:109], v[138:141], v[188:191], 0
	v_mfma_f32_16x16x32_bf16 v[94:97], v[130:133], v[196:199], 0
	v_mfma_f32_16x16x32_bf16 v[90:93], v[138:141], v[196:199], 0
	v_mfma_f32_16x16x32_bf16 v[82:85], v[130:133], v[204:207], 0
	v_mfma_f32_16x16x32_bf16 v[74:77], v[138:141], v[204:207], 0
	v_mfma_f32_16x16x32_bf16 v[126:129], v[134:137], v[150:153], v[126:129]
	v_mfma_f32_16x16x32_bf16 v[122:125], v[142:145], v[150:153], v[122:125]
	v_mfma_f32_16x16x32_bf16 v[114:117], v[134:137], v[192:195], v[114:117]
	v_mfma_f32_16x16x32_bf16 v[106:109], v[142:145], v[192:195], v[106:109]
	v_mfma_f32_16x16x32_bf16 v[94:97], v[134:137], v[200:203], v[94:97]
	v_mfma_f32_16x16x32_bf16 v[90:93], v[142:145], v[200:203], v[90:93]
	v_mfma_f32_16x16x32_bf16 v[82:85], v[134:137], v[218:221], v[82:85]
	v_mfma_f32_16x16x32_bf16 v[74:77], v[142:145], v[218:221], v[74:77]

; #define PG8_STAGE(bufoff, gbase, voff) do { _Pragma("unroll") for (int _i = 0; _i < 2; ++_i) \
;         __builtin_amdgcn_global_load_lds((const unsigned*)((const char*)(gbase) + (voff)[_i]), (LAS unsigned*)(lds + (bufoff) + ldsw + _i * 8192), 16, 0, 0); } while (0)
; #define PG8_MMA(ai, bj, At, Bt) do { __builtin_amdgcn_s_setprio(1); _Pragma("unroll") for (int m = 0; m < 4; ++m) _Pragma("unroll") for (int n = 0; n < 2; ++n) _Pragma("unroll") for (int k = 0; k < 2; ++k) \
;         acc[ai][bj][m][n] = __builtin_amdgcn_mfma_f32_16x16x32_bf16(Bt[n][k], At[m][k], acc[ai][bj][m][n], 0, 0, 0); __builtin_amdgcn_s_setprio(0); } while (0)
; #define PG8_WAIT_V(n) asm volatile("s_waitcnt vmcnt(" #n ")" ::: "memory")
; #define PG8_BAR __builtin_amdgcn_s_barrier()
; template <class Epi>
; DEVI void gemm_phase(LAS unsigned char* lds, const Gemm g, const Epi& E) {
;     ...
;             PG8_STAGE(PG8_SB(0, 1), b2 + hstepB, voffB);
;             PG8_WAIT_V(6); PG8_BAR; PG8_MMA(1, 1, At, B1); PG8_BAR;
.Lip13l_a_2:
	s_barrier
	s_add_u32 s26, s46, 0x40000
	s_addc_u32 s27, s47, 0
	s_add_i32 s19, s19, s80
	s_mov_b32 m0, s19
	v_lshl_add_u64 v[130:131], s[26:27], 0, v[178:179]
	global_load_lds_dwordx4 v[130:131], off
	s_add_i32 m0, s19, 0x2000
	v_lshl_add_u64 v[130:131], s[26:27], 0, v[182:183]
	global_load_lds_dwordx4 v[130:131], off
	s_waitcnt vmcnt(6)
	ds_write_b128 v249, v[244:247]
	s_barrier
	s_cmp_lg_u32 s100, 0
	s_cbranch_scc1 .Lip13l_a_3
	v_mfma_f32_16x16x32_bf16 v[50:53], v[222:225], v[146:149], 0
	v_mfma_f32_16x16x32_bf16 v[54:57], v[230:233], v[146:149], 0
	v_mfma_f32_16x16x32_bf16 v[34:37], v[222:225], v[188:191], 0
	v_mfma_f32_16x16x32_bf16 v[38:41], v[230:233], v[188:191], 0
	v_mfma_f32_16x16x32_bf16 v[18:21], v[222:225], v[196:199], 0
	v_mfma_f32_16x16x32_bf16 v[22:25], v[230:233], v[196:199], 0
	v_mfma_f32_16x16x32_bf16 v[0:3], v[222:225], v[204:207], 0
	v_mfma_f32_16x16x32_bf16 v[4:7], v[230:233], v[204:207], 0
	v_mfma_f32_16x16x32_bf16 v[50:53], v[226:229], v[150:153], v[50:53]
	v_mfma_f32_16x16x32_bf16 v[54:57], v[234:237], v[150:153], v[54:57]
	v_mfma_f32_16x16x32_bf16 v[34:37], v[226:229], v[192:195], v[34:37]
	v_mfma_f32_16x16x32_bf16 v[38:41], v[234:237], v[192:195], v[38:41]
	v_mfma_f32_16x16x32_bf16 v[18:21], v[226:229], v[200:203], v[18:21]
	v_mfma_f32_16x16x32_bf16 v[22:25], v[234:237], v[200:203], v[22:25]
	v_mfma_f32_16x16x32_bf16 v[0:3], v[226:229], v[218:221], v[0:3]
	v_mfma_f32_16x16x32_bf16 v[4:7], v[234:237], v[218:221], v[4:7]

; template <class Epi>
; DEVI void gemm_phase(LAS unsigned char* lds, const Gemm g, const Epi& E) {
;     ...
;             const int row0 = cur.pm * BM + wr * 64 + fr, col0 = cur.pn * BM + wc * 32 + (Epi::PERM ? 8 : 4) * fq; constexpr int NST = Epi::PERM ? 4 : 16;
;             float rsv[8];
;             if constexpr (Epi::RS) { f32x4 q4[8];
; #pragma unroll
;                 for (int i = 0; i < 8; ++i) q4[i] = *(const f32x4*)(E.ssq_in + (size_t)(row0 + (i >> 2) * HALF + (i & 3) * 16) * 4);
; #pragma unroll
;                 for (int i = 0; i < 8; ++i) rsv[i] = rsqrtf((((q4[i][0] + q4[i][1]) + q4[i][2]) + q4[i][3]) * (1.f / DM) + 1e-6f); }
.Lip13l_a_out:
	v_lshlrev_b32_e32 v255, 4, v213
	v_add_u32_e32 v255, 0x21000, v255
	s_setprio 0
	v_lshl_add_u32 v204, s6, 8, v213
	v_add_u32_e32 v188, 0xb0, v204
	v_ashrrev_i32_e32 v205, 31, v204
	v_or_b32_e32 v202, 16, v204
	v_ashrrev_i32_e32 v189, 31, v188
	v_lshl_add_u64 v[130:131], v[204:205], 4, s[76:77]
	v_ashrrev_i32_e32 v203, 31, v202
	v_lshl_add_u64 v[134:135], v[188:189], 4, s[76:77]
	ds_read_b128 v[206:209], v255
	v_or_b32_e32 v200, 32, v204
	ds_read_b128 v[134:137], v255 offset:2816
	v_lshl_add_u64 v[130:131], v[202:203], 4, s[76:77]
	ds_read_b128 v[218:221], v255 offset:256
	v_ashrrev_i32_e32 v201, 31, v200
	v_or_b32_e32 v198, 48, v204
	v_lshl_add_u64 v[130:131], v[200:201], 4, s[76:77]
	v_ashrrev_i32_e32 v199, 31, v198
	v_add_u32_e32 v196, 0x80, v204
	ds_read_b128 v[146:149], v255 offset:512
	v_lshl_add_u64 v[130:131], v[198:199], 4, s[76:77]
	v_ashrrev_i32_e32 v197, 31, v196
	v_add_u32_e32 v194, 0x90, v204
	ds_read_b128 v[150:153], v255 offset:768
	v_lshl_add_u64 v[130:131], v[196:197], 4, s[76:77]
	v_ashrrev_i32_e32 v195, 31, v194
	v_add_u32_e32 v192, 0xa0, v204
	ds_read_b128 v[138:141], v255 offset:2048
	v_lshl_add_u64 v[130:131], v[194:195], 4, s[76:77]
	v_ashrrev_i32_e32 v193, 31, v192
	ds_read_b128 v[142:145], v255 offset:2304
	v_lshl_add_u64 v[130:131], v[192:193], 4, s[76:77]
	ds_read_b128 v[130:133], v255 offset:2560
	s_waitcnt lgkmcnt(0)
	v_mov_b32_e32 v191, v206
	v_mov_b32_e32 v190, v218
	v_mov_b32_e32 v206, v219
	v_pk_add_f32 v[190:191], v[190:191], v[206:207]
	v_mov_b32_e32 v206, v220
	v_mov_b32_e32 v207, v208
	v_pk_add_f32 v[190:191], v[206:207], v[190:191]
	v_mov_b32_e32 v208, v221
	v_pk_add_f32 v[190:191], v[208:209], v[190:191]
	s_nop 0
	v_pk_fma_f32 v[206:207], v[190:191], s[72:73], v[160:161] op_sel_hi:[1,0,0]
	v_lshl_or_b32 v190, s4, 8, v215
	v_mul_f32_e32 v8, 0x4b800000, v207
	v_cmp_gt_f32_e32 vcc, s94, v207
	v_cmp_gt_f32_e64 s[6:7], s94, v206
	s_nop 0
	v_cndmask_b32_e32 v8, v207, v8, vcc
	v_rsq_f32_e32 v8, v8
	s_nop 0
	v_mul_f32_e32 v162, 0x45800000, v8
	v_cndmask_b32_e32 v208, v8, v162, vcc
	v_pk_mul_f32 v[128:129], v[128:129], v[208:209] op_sel_hi:[1,0]
	v_pk_mul_f32 v[126:127], v[126:127], v[208:209] op_sel_hi:[1,0]
	v_pk_mul_f32 v[124:125], v[124:125], v[208:209] op_sel_hi:[1,0]
	v_pk_mul_f32 v[122:123], v[122:123], v[208:209] op_sel_hi:[1,0]
	v_cmp_lt_i32_e32 vcc, s39, v190
	v_add_u32_e32 v8, 0xfffff400, v190
	s_and_saveexec_b64 s[0:1], vcc
	s_xor_b64 s[8:9], exec, s[0:1]
	s_cbranch_execz .LBB0_281
	v_cmp_gt_u32_e64 s[4:5], 16, v8
	s_and_saveexec_b64 s[46:47], s[4:5]
	s_cbranch_execz .LBB0_280
	v_lshlrev_b64 v[218:219], 6, v[204:205]
	v_lshl_add_u64 v[218:219], s[58:59], 0, v[218:219]
	v_lshl_add_u64 v[218:219], v[8:9], 2, v[218:219]
	global_store_dwordx4 v[218:219], v[126:129], off
	global_store_dwordx4 v[218:219], v[122:125], off offset:16

; DEVI size_t gemm_offB(const Gemm& g, const Unit& u) { return (g.split ? (size_t)(u.b >> 2) * g.sB + (size_t)(u.b & 3) * g.sB_lo : (size_t)u.b * g.sB) + (size_t)(u.pm >> g.pmsh) * g.sBpm; }
; #define PG8_STAGE(bufoff, gbase, voff) do { _Pragma("unroll") for (int _i = 0; _i < 2; ++_i) \
;         __builtin_amdgcn_global_load_lds((const unsigned*)((const char*)(gbase) + (voff)[_i]), (LAS unsigned*)(lds + (bufoff) + ldsw + _i * 8192), 16, 0, 0); } while (0)
; #define PG8_LDA(dst, b, h) do { _Pragma("unroll") for (int m = 0; m < 4; ++m) _Pragma("unroll") for (int k = 0; k < 2; ++k) dst[m][k] = *(const LAS bf16x8*)(lds + PG8_SA(b, h) + aoff + m * 2048 + k * 1024); } while (0)
; #define PG8_LDB(dst, b, h) do { _Pragma("unroll") for (int n = 0; n < 2; ++n) _Pragma("unroll") for (int k = 0; k < 2; ++k) dst[n][k] = *(const LAS bf16x8*)(lds + PG8_SB(b, h) + boff + n * 2048 + k * 1024); } while (0)
; #define PG8_WAIT_L(n) asm volatile("s_waitcnt lgkmcnt(" #n ")" ::: "memory")
; #define PG8_BAR __builtin_amdgcn_s_barrier()
; #define PG8_SCHED __builtin_amdgcn_sched_barrier(0)
; template <class Epi>
; DEVI void gemm_phase(LAS unsigned char* lds, const Gemm g, const Epi& E) {
;     ...
;         const bool has_next = unit_next(g, ui + 1, nxt);
;         const char* nA = has_next ? (const char*)g.A + gemm_offA(g, nxt) * 2 + (size_t)nxt.pm * tstepA : cA;
;         const char* nB = has_next ? (const char*)g.Bt + gemm_offB(g, nxt) * 2 + (size_t)nxt.pn * tstepB : cB;
;         for (int t = 0; t < nt; t += 2) {
;             const bool last = (t == nt - 2);
;             const char* a1 = cA + (size_t)(t + 1) * kstep;
;             const char* a2 = last ? nA : cA + (size_t)(t + 2) * kstep; const char* b2 = last ? nB : cB + (size_t)(t + 2) * kstep;
;             const char* a3 = a2 + kstep; const char* b3 = b2 + kstep;
;             PG8_LDB(B0, 0, 0); PG8_SCHED; PG8_LDA(At, 0, 0); PG8_STAGE(PG8_SA(1, 1), a1 + hstepA, voffA);
;             PG8_WAIT_L(8); PG8_BAR; PG8_WAIT_L(0); PG8_MMA(0, 0, At, B0); PG8_BAR; PG8_SCHED;
;             PG8_LDB(B1, 0, 1); PG8_STAGE(PG8_SB(0, 0), b2, voffB);
;             PG8_BAR; PG8_WAIT_L(0); PG8_MMA(0, 1, At, B1); PG8_BAR;
;             PG8_LDA(At, 0, 1); PG8_STAGE(PG8_SA(0, 0), a2, voffA);
;             PG8_BAR; PG8_WAIT_L(0); PG8_MMA(1, 0, At, B0); PG8_BAR; PG8_SCHED;
.LBB0_355:
	s_ashr_i32 s11, s10, 31
	v_mov_b64_e32 v[0:1], 0x680
	s_lshl_b64 s[0:1], s[10:11], 19
	v_cmp_lt_i64_e32 vcc, s[14:15], v[0:1]
	s_add_u32 s14, s24, s0
	s_addc_u32 s15, s25, s1
	s_and_b64 s[0:1], vcc, exec
	s_cselect_b32 s0, s15, s9
	s_cselect_b32 s1, s14, s8
	s_ashr_i32 s13, s12, 31
	s_lshl_b64 s[16:17], s[12:13], 19
	s_add_u32 s16, s82, s16
	s_addc_u32 s17, s83, s17
	s_and_b64 s[18:19], vcc, exec
	s_cselect_b32 s5, s17, s47
	s_cselect_b32 s7, s16, s46
	s_add_u32 s8, s8, 0x40080
	s_addc_u32 s9, s9, 0
	s_add_u32 s11, s46, 0x100
	s_addc_u32 s13, s47, 0
	s_mov_b32 s18, -2
	s_cmp_eq_u32 s4, 12
	s_cbranch_scc1 .Lip13l_b_in
	v_and_b32_e32 v248, 0xff, v154
	v_lshlrev_b32_e32 v248, 4, v248
	v_add_u32_e32 v249, 0x21000, v248
	v_lshl_add_u32 v248, s6, 12, v248
	global_load_dwordx4 v[244:247], v248, s[76:77]
	s_add_u32 s19, s8, 0xfffc0080
	s_addc_u32 s26, s9, -1
	s_add_i32 s27, 0, 0x10000
	v_add_u32_e32 v142, s27, v209
	ds_read_b128 v[130:133], v142
	ds_read_b128 v[134:137], v142 offset:1024
	ds_read_b128 v[138:141], v142 offset:2048
	ds_read_b128 v[142:145], v142 offset:3072
	s_cmp_eq_u32 s18, 12
	s_cselect_b32 s69, s0, s26
	s_cselect_b32 s68, s1, s19
	s_cselect_b32 s47, s5, s13
	s_cselect_b32 s46, s7, s11
	v_lshl_add_u64 v[206:207], s[8:9], 0, v[182:183]
	s_add_i32 m0, s85, 0xc000
	ds_read_b128 v[146:149], v214
	ds_read_b128 v[150:153], v214 offset:1024
	ds_read_b128 v[186:189], v214 offset:2048
	ds_read_b128 v[190:193], v214 offset:3072
	ds_read_b128 v[194:197], v214 offset:4096
	ds_read_b128 v[198:201], v214 offset:5120
	ds_read_b128 v[202:205], v214 offset:6144
	ds_read_b128 v[216:219], v214 offset:7168
	global_load_lds_dwordx4 v[206:207], off
	s_add_i32 m0, s85, 0xe000
	v_lshl_add_u64 v[206:207], s[8:9], 0, v[184:185]
	global_load_lds_dwordx4 v[206:207], off
	s_waitcnt lgkmcnt(8)
	s_barrier
	s_waitcnt lgkmcnt(0)
	v_mfma_f32_16x16x32_bf16 v[126:129], v[130:133], v[146:149], 0
	v_mfma_f32_16x16x32_bf16 v[122:125], v[138:141], v[146:149], 0
	v_mfma_f32_16x16x32_bf16 v[114:117], v[130:133], v[186:189], 0
	v_mfma_f32_16x16x32_bf16 v[106:109], v[138:141], v[186:189], 0
	v_mfma_f32_16x16x32_bf16 v[94:97], v[130:133], v[194:197], 0
	v_mfma_f32_16x16x32_bf16 v[90:93], v[138:141], v[194:197], 0
	v_mfma_f32_16x16x32_bf16 v[82:85], v[130:133], v[202:205], 0
	v_mfma_f32_16x16x32_bf16 v[74:77], v[138:141], v[202:205], 0
	v_mfma_f32_16x16x32_bf16 v[126:129], v[134:137], v[150:153], v[126:129]
	v_mfma_f32_16x16x32_bf16 v[122:125], v[142:145], v[150:153], v[122:125]
	v_mfma_f32_16x16x32_bf16 v[114:117], v[134:137], v[190:193], v[114:117]
	v_mfma_f32_16x16x32_bf16 v[106:109], v[142:145], v[190:193], v[106:109]
	v_mfma_f32_16x16x32_bf16 v[94:97], v[134:137], v[198:201], v[94:97]
	v_mfma_f32_16x16x32_bf16 v[90:93], v[142:145], v[198:201], v[90:93]
	v_mfma_f32_16x16x32_bf16 v[82:85], v[134:137], v[216:219], v[82:85]
	v_mfma_f32_16x16x32_bf16 v[74:77], v[142:145], v[216:219], v[74:77]
	s_barrier
	s_add_i32 s19, 0, 0x14000
	s_add_i32 s26, s27, s84
	v_add_u32_e32 v162, s19, v209
	v_lshl_add_u64 v[206:207], s[46:47], 0, v[8:9]
	s_mov_b32 m0, s26
	ds_read_b128 v[220:223], v162
	ds_read_b128 v[224:227], v162 offset:1024
	ds_read_b128 v[228:231], v162 offset:2048
	ds_read_b128 v[232:235], v162 offset:3072
	global_load_lds_dwordx4 v[206:207], off
	s_add_i32 m0, s26, 0x2000
	v_lshl_add_u64 v[236:237], s[46:47], 0, v[180:181]
	global_load_lds_dwordx4 v[236:237], off
	s_barrier
	s_waitcnt lgkmcnt(0)
	v_mfma_f32_16x16x32_bf16 v[118:121], v[220:223], v[146:149], 0
	v_mfma_f32_16x16x32_bf16 v[110:113], v[228:231], v[146:149], 0
	v_mfma_f32_16x16x32_bf16 v[102:105], v[220:223], v[186:189], 0
	v_mfma_f32_16x16x32_bf16 v[98:101], v[228:231], v[186:189], 0
	v_mfma_f32_16x16x32_bf16 v[86:89], v[220:223], v[194:197], 0
	v_mfma_f32_16x16x32_bf16 v[78:81], v[228:231], v[194:197], 0
	v_mfma_f32_16x16x32_bf16 v[62:65], v[220:223], v[202:205], 0
	v_mfma_f32_16x16x32_bf16 v[58:61], v[228:231], v[202:205], 0
	v_mfma_f32_16x16x32_bf16 v[118:121], v[224:227], v[150:153], v[118:121]
	v_mfma_f32_16x16x32_bf16 v[110:113], v[232:235], v[150:153], v[110:113]
	v_mfma_f32_16x16x32_bf16 v[102:105], v[224:227], v[190:193], v[102:105]
	v_mfma_f32_16x16x32_bf16 v[98:101], v[232:235], v[190:193], v[98:101]
	v_mfma_f32_16x16x32_bf16 v[86:89], v[224:227], v[198:201], v[86:89]
	v_mfma_f32_16x16x32_bf16 v[78:81], v[232:235], v[198:201], v[78:81]
	v_mfma_f32_16x16x32_bf16 v[62:65], v[224:227], v[216:219], v[62:65]
	v_mfma_f32_16x16x32_bf16 v[58:61], v[232:235], v[216:219], v[58:61]
	s_mov_b32 m0, s85
	v_lshl_add_u64 v[238:239], s[68:69], 0, v[176:177]
	s_barrier
	ds_read_b128 v[146:149], v214 offset:16384
	ds_read_b128 v[150:153], v214 offset:17408
	ds_read_b128 v[186:189], v214 offset:18432
	ds_read_b128 v[190:193], v214 offset:19456
	ds_read_b128 v[194:197], v214 offset:20480
	ds_read_b128 v[198:201], v214 offset:21504
	ds_read_b128 v[202:205], v214 offset:22528
	ds_read_b128 v[216:219], v214 offset:23552
	global_load_lds_dwordx4 v[238:239], off
	s_mov_b32 m0, s86
	v_lshl_add_u64 v[240:241], s[68:69], 0, v[178:179]
	global_load_lds_dwordx4 v[240:241], off
	s_barrier
; #define PG8_STAGE(bufoff, gbase, voff) do { _Pragma("unroll") for (int _i = 0; _i < 2; ++_i) \
;         __builtin_amdgcn_global_load_lds((const unsigned*)((const char*)(gbase) + (voff)[_i]), (LAS unsigned*)(lds + (bufoff) + ldsw + _i * 8192), 16, 0, 0); } while (0)
; #define PG8_LDA(dst, b, h) do { _Pragma("unroll") for (int m = 0; m < 4; ++m) _Pragma("unroll") for (int k = 0; k < 2; ++k) dst[m][k] = *(const LAS bf16x8*)(lds + PG8_SA(b, h) + aoff + m * 2048 + k * 1024); } while (0)
; #define PG8_LDB(dst, b, h) do { _Pragma("unroll") for (int n = 0; n < 2; ++n) _Pragma("unroll") for (int k = 0; k < 2; ++k) dst[n][k] = *(const LAS bf16x8*)(lds + PG8_SB(b, h) + boff + n * 2048 + k * 1024); } while (0)
; #define PG8_MMA(ai, bj, At, Bt) do { __builtin_amdgcn_s_setprio(1); _Pragma("unroll") for (int m = 0; m < 4; ++m) _Pragma("unroll") for (int n = 0; n < 2; ++n) _Pragma("unroll") for (int k = 0; k < 2; ++k) \
;         acc[ai][bj][m][n] = __builtin_amdgcn_mfma_f32_16x16x32_bf16(Bt[n][k], At[m][k], acc[ai][bj][m][n], 0, 0, 0); __builtin_amdgcn_s_setprio(0); } while (0)
; #define PG8_WAIT_V(n) asm volatile("s_waitcnt vmcnt(" #n ")" ::: "memory")
; #define PG8_WAIT_L(n) asm volatile("s_waitcnt lgkmcnt(" #n ")" ::: "memory")
; #define PG8_BAR __builtin_amdgcn_s_barrier()
; #define PG8_SCHED __builtin_amdgcn_sched_barrier(0)
; template <class Epi>
; DEVI void gemm_phase(LAS unsigned char* lds, const Gemm g, const Epi& E) {
;     ...
;             PG8_BAR; PG8_WAIT_L(0); PG8_MMA(1, 0, At, B0); PG8_BAR; PG8_SCHED;
;             PG8_STAGE(PG8_SB(0, 1), b2 + hstepB, voffB);
;             PG8_WAIT_V(6); PG8_BAR; PG8_MMA(1, 1, At, B1); PG8_BAR;
;             PG8_LDB(B0, 1, 0); PG8_SCHED; PG8_LDA(At, 1, 0); PG8_STAGE(PG8_SA(0, 1), a2 + hstepA, voffA);
;             PG8_WAIT_L(8); PG8_BAR; PG8_WAIT_L(0); PG8_MMA(0, 0, At, B0); PG8_BAR; PG8_SCHED;
;             PG8_LDB(B1, 1, 1); PG8_STAGE(PG8_SB(1, 0), b3, voffB);
;             PG8_BAR; PG8_WAIT_L(0); PG8_MMA(0, 1, At, B1); PG8_BAR;
;             PG8_LDA(At, 1, 1); PG8_STAGE(PG8_SA(1, 0), a3, voffA);
;             PG8_BAR; PG8_WAIT_L(0); PG8_MMA(1, 0, At, B0); PG8_BAR; PG8_SCHED;
	s_waitcnt lgkmcnt(0)
	v_mfma_f32_16x16x32_bf16 v[70:73], v[130:133], v[146:149], 0
	v_mfma_f32_16x16x32_bf16 v[66:69], v[138:141], v[146:149], 0
	v_mfma_f32_16x16x32_bf16 v[46:49], v[130:133], v[186:189], 0
	v_mfma_f32_16x16x32_bf16 v[42:45], v[138:141], v[186:189], 0
	v_mfma_f32_16x16x32_bf16 v[30:33], v[130:133], v[194:197], 0
	v_mfma_f32_16x16x32_bf16 v[26:29], v[138:141], v[194:197], 0
	v_mfma_f32_16x16x32_bf16 v[14:17], v[130:133], v[202:205], 0
	v_mfma_f32_16x16x32_bf16 v[10:13], v[138:141], v[202:205], 0
	v_mfma_f32_16x16x32_bf16 v[70:73], v[134:137], v[150:153], v[70:73]
	v_mfma_f32_16x16x32_bf16 v[66:69], v[142:145], v[150:153], v[66:69]
	v_mfma_f32_16x16x32_bf16 v[46:49], v[134:137], v[190:193], v[46:49]
	v_mfma_f32_16x16x32_bf16 v[42:45], v[142:145], v[190:193], v[42:45]
	v_mfma_f32_16x16x32_bf16 v[30:33], v[134:137], v[198:201], v[30:33]
	v_mfma_f32_16x16x32_bf16 v[26:29], v[142:145], v[198:201], v[26:29]
	v_mfma_f32_16x16x32_bf16 v[14:17], v[134:137], v[216:219], v[14:17]
	v_mfma_f32_16x16x32_bf16 v[10:13], v[142:145], v[216:219], v[10:13]
	s_barrier
	s_add_u32 s26, s46, 0x40000
	s_addc_u32 s27, s47, 0
	s_add_i32 s19, s19, s84
	s_mov_b32 m0, s19
	v_lshl_add_u64 v[130:131], s[26:27], 0, v[8:9]
	global_load_lds_dwordx4 v[130:131], off
	s_add_i32 m0, s19, 0x2000
	v_lshl_add_u64 v[130:131], s[26:27], 0, v[180:181]
	global_load_lds_dwordx4 v[130:131], off
	s_waitcnt vmcnt(6)
	ds_write_b128 v249, v[244:247]
	s_barrier
	v_mfma_f32_16x16x32_bf16 v[50:53], v[220:223], v[146:149], 0
	v_mfma_f32_16x16x32_bf16 v[54:57], v[228:231], v[146:149], 0
	v_mfma_f32_16x16x32_bf16 v[34:37], v[220:223], v[186:189], 0
	v_mfma_f32_16x16x32_bf16 v[38:41], v[228:231], v[186:189], 0
	v_mfma_f32_16x16x32_bf16 v[18:21], v[220:223], v[194:197], 0
	v_mfma_f32_16x16x32_bf16 v[22:25], v[228:231], v[194:197], 0
	v_mfma_f32_16x16x32_bf16 v[0:3], v[220:223], v[202:205], 0
	v_mfma_f32_16x16x32_bf16 v[4:7], v[228:231], v[202:205], 0
	v_mfma_f32_16x16x32_bf16 v[50:53], v[224:227], v[150:153], v[50:53]
	v_mfma_f32_16x16x32_bf16 v[54:57], v[232:235], v[150:153], v[54:57]
	v_mfma_f32_16x16x32_bf16 v[34:37], v[224:227], v[190:193], v[34:37]
	v_mfma_f32_16x16x32_bf16 v[38:41], v[232:235], v[190:193], v[38:41]
	v_mfma_f32_16x16x32_bf16 v[18:21], v[224:227], v[198:201], v[18:21]
	v_mfma_f32_16x16x32_bf16 v[22:25], v[232:235], v[198:201], v[22:25]
	v_mfma_f32_16x16x32_bf16 v[0:3], v[224:227], v[216:219], v[0:3]
	v_mfma_f32_16x16x32_bf16 v[4:7], v[232:235], v[216:219], v[4:7]
	s_add_i32 s19, 0, 0x18000
	v_add_u32_e32 v142, s19, v209
	s_barrier
	ds_read_b128 v[130:133], v142
	ds_read_b128 v[134:137], v142 offset:1024
	ds_read_b128 v[138:141], v142 offset:2048
	ds_read_b128 v[142:145], v142 offset:3072
	s_add_u32 s26, s68, 0x40000
	s_addc_u32 s27, s69, 0
	s_mov_b32 m0, s87
	v_lshl_add_u64 v[220:221], s[26:27], 0, v[176:177]
	ds_read_b128 v[146:149], v214 offset:32768
	ds_read_b128 v[150:153], v214 offset:33792
	ds_read_b128 v[186:189], v214 offset:34816
	ds_read_b128 v[190:193], v214 offset:35840
	ds_read_b128 v[194:197], v214 offset:36864
	ds_read_b128 v[198:201], v214 offset:37888
	ds_read_b128 v[202:205], v214 offset:38912
	ds_read_b128 v[216:219], v214 offset:39936
	global_load_lds_dwordx4 v[220:221], off
	s_mov_b32 m0, s88
	v_lshl_add_u64 v[220:221], s[26:27], 0, v[178:179]
	global_load_lds_dwordx4 v[220:221], off
	s_waitcnt lgkmcnt(8)
	s_barrier
	s_waitcnt lgkmcnt(0)
	v_mfma_f32_16x16x32_bf16 v[126:129], v[130:133], v[146:149], v[126:129]
	v_mfma_f32_16x16x32_bf16 v[122:125], v[138:141], v[146:149], v[122:125]
	v_mfma_f32_16x16x32_bf16 v[114:117], v[130:133], v[186:189], v[114:117]
	v_mfma_f32_16x16x32_bf16 v[106:109], v[138:141], v[186:189], v[106:109]
	v_mfma_f32_16x16x32_bf16 v[94:97], v[130:133], v[194:197], v[94:97]
	v_mfma_f32_16x16x32_bf16 v[90:93], v[138:141], v[194:197], v[90:93]
	v_mfma_f32_16x16x32_bf16 v[82:85], v[130:133], v[202:205], v[82:85]
	v_mfma_f32_16x16x32_bf16 v[74:77], v[138:141], v[202:205], v[74:77]
	v_mfma_f32_16x16x32_bf16 v[126:129], v[134:137], v[150:153], v[126:129]
	v_mfma_f32_16x16x32_bf16 v[122:125], v[142:145], v[150:153], v[122:125]
	v_mfma_f32_16x16x32_bf16 v[114:117], v[134:137], v[190:193], v[114:117]
	v_mfma_f32_16x16x32_bf16 v[106:109], v[142:145], v[190:193], v[106:109]
	v_mfma_f32_16x16x32_bf16 v[94:97], v[134:137], v[198:201], v[94:97]
	v_mfma_f32_16x16x32_bf16 v[90:93], v[142:145], v[198:201], v[90:93]
	v_mfma_f32_16x16x32_bf16 v[82:85], v[134:137], v[216:219], v[82:85]
	v_mfma_f32_16x16x32_bf16 v[74:77], v[142:145], v[216:219], v[74:77]
	s_barrier
; #define PG8_STAGE(bufoff, gbase, voff) do { _Pragma("unroll") for (int _i = 0; _i < 2; ++_i) \
;         __builtin_amdgcn_global_load_lds((const unsigned*)((const char*)(gbase) + (voff)[_i]), (LAS unsigned*)(lds + (bufoff) + ldsw + _i * 8192), 16, 0, 0); } while (0)
; #define PG8_LDA(dst, b, h) do { _Pragma("unroll") for (int m = 0; m < 4; ++m) _Pragma("unroll") for (int k = 0; k < 2; ++k) dst[m][k] = *(const LAS bf16x8*)(lds + PG8_SA(b, h) + aoff + m * 2048 + k * 1024); } while (0)
; #define PG8_LDB(dst, b, h) do { _Pragma("unroll") for (int n = 0; n < 2; ++n) _Pragma("unroll") for (int k = 0; k < 2; ++k) dst[n][k] = *(const LAS bf16x8*)(lds + PG8_SB(b, h) + boff + n * 2048 + k * 1024); } while (0)
; #define PG8_MMA(ai, bj, At, Bt) do { __builtin_amdgcn_s_setprio(1); _Pragma("unroll") for (int m = 0; m < 4; ++m) _Pragma("unroll") for (int n = 0; n < 2; ++n) _Pragma("unroll") for (int k = 0; k < 2; ++k) \
;         acc[ai][bj][m][n] = __builtin_amdgcn_mfma_f32_16x16x32_bf16(Bt[n][k], At[m][k], acc[ai][bj][m][n], 0, 0, 0); __builtin_amdgcn_s_setprio(0); } while (0)
; #define PG8_WAIT_V(n) asm volatile("s_waitcnt vmcnt(" #n ")" ::: "memory")
; #define PG8_WAIT_L(n) asm volatile("s_waitcnt lgkmcnt(" #n ")" ::: "memory")
; #define PG8_BAR __builtin_amdgcn_s_barrier()
; #define PG8_SCHED __builtin_amdgcn_sched_barrier(0)
; template <class Epi>
; DEVI void gemm_phase(LAS unsigned char* lds, const Gemm g, const Epi& E) {
;     ...
;             PG8_LDB(B0, 1, 0); PG8_SCHED; PG8_LDA(At, 1, 0); PG8_STAGE(PG8_SA(0, 1), a2 + hstepA, voffA);
;             PG8_WAIT_L(8); PG8_BAR; PG8_WAIT_L(0); PG8_MMA(0, 0, At, B0); PG8_BAR; PG8_SCHED;
;             PG8_LDB(B1, 1, 1); PG8_STAGE(PG8_SB(1, 0), b3, voffB);
;             PG8_BAR; PG8_WAIT_L(0); PG8_MMA(0, 1, At, B1); PG8_BAR;
;             PG8_LDA(At, 1, 1); PG8_STAGE(PG8_SA(1, 0), a3, voffA);
;             PG8_BAR; PG8_WAIT_L(0); PG8_MMA(1, 0, At, B0); PG8_BAR; PG8_SCHED;
;             PG8_STAGE(PG8_SB(1, 1), b3 + hstepB, voffB);
;             PG8_WAIT_V(6); PG8_BAR; PG8_MMA(1, 1, At, B1); PG8_BAR;
;         }
	s_add_i32 s38, 0, 0x1c000
	s_add_i32 s19, s19, s84
	v_add_u32_e32 v162, s38, v209
	v_lshl_add_u64 v[206:207], v[206:207], 0, s[70:71]
	s_mov_b32 m0, s19
	ds_read_b128 v[220:223], v162
	ds_read_b128 v[224:227], v162 offset:1024
	ds_read_b128 v[228:231], v162 offset:2048
	ds_read_b128 v[232:235], v162 offset:3072
	global_load_lds_dwordx4 v[206:207], off
	s_add_i32 m0, s19, 0x2000
	v_lshl_add_u64 v[206:207], v[236:237], 0, s[70:71]
	global_load_lds_dwordx4 v[206:207], off
	s_barrier
	s_waitcnt lgkmcnt(0)
	v_mfma_f32_16x16x32_bf16 v[118:121], v[220:223], v[146:149], v[118:121]
	v_mfma_f32_16x16x32_bf16 v[110:113], v[228:231], v[146:149], v[110:113]
	v_mfma_f32_16x16x32_bf16 v[102:105], v[220:223], v[186:189], v[102:105]
	v_mfma_f32_16x16x32_bf16 v[98:101], v[228:231], v[186:189], v[98:101]
	v_mfma_f32_16x16x32_bf16 v[86:89], v[220:223], v[194:197], v[86:89]
	v_mfma_f32_16x16x32_bf16 v[78:81], v[228:231], v[194:197], v[78:81]
	v_mfma_f32_16x16x32_bf16 v[62:65], v[220:223], v[202:205], v[62:65]
	v_mfma_f32_16x16x32_bf16 v[58:61], v[228:231], v[202:205], v[58:61]
	v_mfma_f32_16x16x32_bf16 v[118:121], v[224:227], v[150:153], v[118:121]
	v_mfma_f32_16x16x32_bf16 v[110:113], v[232:235], v[150:153], v[110:113]
	v_mfma_f32_16x16x32_bf16 v[102:105], v[224:227], v[190:193], v[102:105]
	v_mfma_f32_16x16x32_bf16 v[98:101], v[232:235], v[190:193], v[98:101]
	v_mfma_f32_16x16x32_bf16 v[86:89], v[224:227], v[198:201], v[86:89]
	v_mfma_f32_16x16x32_bf16 v[78:81], v[232:235], v[198:201], v[78:81]
	v_mfma_f32_16x16x32_bf16 v[62:65], v[224:227], v[216:219], v[62:65]
	v_mfma_f32_16x16x32_bf16 v[58:61], v[232:235], v[216:219], v[58:61]
	s_mov_b32 m0, s89
	v_lshl_add_u64 v[206:207], v[238:239], 0, s[70:71]
	s_barrier
	ds_read_b128 v[146:149], v214 offset:49152
	ds_read_b128 v[150:153], v214 offset:50176
	ds_read_b128 v[186:189], v214 offset:51200
	ds_read_b128 v[190:193], v214 offset:52224
	ds_read_b128 v[194:197], v214 offset:53248
	ds_read_b128 v[198:201], v214 offset:54272
	ds_read_b128 v[202:205], v214 offset:55296
	ds_read_b128 v[216:219], v214 offset:56320
	global_load_lds_dwordx4 v[206:207], off
	s_mov_b32 m0, s90
	v_lshl_add_u64 v[206:207], v[240:241], 0, s[70:71]
	global_load_lds_dwordx4 v[206:207], off
	s_barrier
	s_waitcnt lgkmcnt(0)
	v_mfma_f32_16x16x32_bf16 v[70:73], v[130:133], v[146:149], v[70:73]
	v_mfma_f32_16x16x32_bf16 v[66:69], v[138:141], v[146:149], v[66:69]
	v_mfma_f32_16x16x32_bf16 v[46:49], v[130:133], v[186:189], v[46:49]
	v_mfma_f32_16x16x32_bf16 v[42:45], v[138:141], v[186:189], v[42:45]
	v_mfma_f32_16x16x32_bf16 v[30:33], v[130:133], v[194:197], v[30:33]
	v_mfma_f32_16x16x32_bf16 v[26:29], v[138:141], v[194:197], v[26:29]
	v_mfma_f32_16x16x32_bf16 v[14:17], v[130:133], v[202:205], v[14:17]
	v_mfma_f32_16x16x32_bf16 v[10:13], v[138:141], v[202:205], v[10:13]
	v_mfma_f32_16x16x32_bf16 v[70:73], v[134:137], v[150:153], v[70:73]
	v_mfma_f32_16x16x32_bf16 v[66:69], v[142:145], v[150:153], v[66:69]
	v_mfma_f32_16x16x32_bf16 v[46:49], v[134:137], v[190:193], v[46:49]
	v_mfma_f32_16x16x32_bf16 v[42:45], v[142:145], v[190:193], v[42:45]
	v_mfma_f32_16x16x32_bf16 v[30:33], v[134:137], v[198:201], v[30:33]
	v_mfma_f32_16x16x32_bf16 v[26:29], v[142:145], v[198:201], v[26:29]
	v_mfma_f32_16x16x32_bf16 v[14:17], v[134:137], v[216:219], v[14:17]
	v_mfma_f32_16x16x32_bf16 v[10:13], v[142:145], v[216:219], v[10:13]
	s_barrier
	s_add_u32 s26, s46, 0x40080
	s_addc_u32 s27, s47, 0
	s_add_i32 s19, s38, s84
	s_mov_b32 m0, s19
	v_lshl_add_u64 v[130:131], s[26:27], 0, v[8:9]
	global_load_lds_dwordx4 v[130:131], off
	s_add_i32 m0, s19, 0x2000
	v_lshl_add_u64 v[130:131], s[26:27], 0, v[180:181]
	global_load_lds_dwordx4 v[130:131], off
	s_waitcnt vmcnt(6)
	s_barrier
	v_mfma_f32_16x16x32_bf16 v[50:53], v[220:223], v[146:149], v[50:53]
	v_mfma_f32_16x16x32_bf16 v[54:57], v[228:231], v[146:149], v[54:57]
	v_mfma_f32_16x16x32_bf16 v[34:37], v[220:223], v[186:189], v[34:37]
	v_mfma_f32_16x16x32_bf16 v[38:41], v[228:231], v[186:189], v[38:41]
	v_mfma_f32_16x16x32_bf16 v[18:21], v[220:223], v[194:197], v[18:21]
	v_mfma_f32_16x16x32_bf16 v[22:25], v[228:231], v[194:197], v[22:25]
	v_mfma_f32_16x16x32_bf16 v[0:3], v[220:223], v[202:205], v[0:3]
	v_mfma_f32_16x16x32_bf16 v[4:7], v[228:231], v[202:205], v[4:7]
	v_mfma_f32_16x16x32_bf16 v[50:53], v[224:227], v[150:153], v[50:53]
	v_mfma_f32_16x16x32_bf16 v[54:57], v[232:235], v[150:153], v[54:57]
	v_mfma_f32_16x16x32_bf16 v[34:37], v[224:227], v[190:193], v[34:37]
	v_mfma_f32_16x16x32_bf16 v[38:41], v[232:235], v[190:193], v[38:41]
	v_mfma_f32_16x16x32_bf16 v[18:21], v[224:227], v[198:201], v[18:21]
	v_mfma_f32_16x16x32_bf16 v[22:25], v[232:235], v[198:201], v[22:25]
	v_mfma_f32_16x16x32_bf16 v[0:3], v[224:227], v[216:219], v[0:3]
	v_mfma_f32_16x16x32_bf16 v[4:7], v[232:235], v[216:219], v[4:7]
	s_add_i32 s18, s18, 2
	s_add_u32 s8, s8, 0x100
	s_addc_u32 s9, s9, 0
	s_add_u32 s11, s11, 0x100
	s_addc_u32 s13, s13, 0
	s_cmp_gt_u32 s18, 13
	s_barrier

; #define PG8_STAGE(bufoff, gbase, voff) do { _Pragma("unroll") for (int _i = 0; _i < 2; ++_i) \
;         __builtin_amdgcn_global_load_lds((const unsigned*)((const char*)(gbase) + (voff)[_i]), (LAS unsigned*)(lds + (bufoff) + ldsw + _i * 8192), 16, 0, 0); } while (0)
; #define PG8_LDA(dst, b, h) do { _Pragma("unroll") for (int m = 0; m < 4; ++m) _Pragma("unroll") for (int k = 0; k < 2; ++k) dst[m][k] = *(const LAS bf16x8*)(lds + PG8_SA(b, h) + aoff + m * 2048 + k * 1024); } while (0)
; #define PG8_LDB(dst, b, h) do { _Pragma("unroll") for (int n = 0; n < 2; ++n) _Pragma("unroll") for (int k = 0; k < 2; ++k) dst[n][k] = *(const LAS bf16x8*)(lds + PG8_SB(b, h) + boff + n * 2048 + k * 1024); } while (0)
; #define PG8_MMA(ai, bj, At, Bt) do { __builtin_amdgcn_s_setprio(1); _Pragma("unroll") for (int m = 0; m < 4; ++m) _Pragma("unroll") for (int n = 0; n < 2; ++n) _Pragma("unroll") for (int k = 0; k < 2; ++k) \
;         acc[ai][bj][m][n] = __builtin_amdgcn_mfma_f32_16x16x32_bf16(Bt[n][k], At[m][k], acc[ai][bj][m][n], 0, 0, 0); __builtin_amdgcn_s_setprio(0); } while (0)
; #define PG8_WAIT_L(n) asm volatile("s_waitcnt lgkmcnt(" #n ")" ::: "memory")
; #define PG8_BAR __builtin_amdgcn_s_barrier()
; #define PG8_SCHED __builtin_amdgcn_sched_barrier(0)
; template <class Epi>
; DEVI void gemm_phase(LAS unsigned char* lds, const Gemm g, const Epi& E) {
;     ...
;             PG8_LDB(B0, 0, 0); PG8_SCHED; PG8_LDA(At, 0, 0); PG8_STAGE(PG8_SA(1, 1), a1 + hstepA, voffA);
;             PG8_WAIT_L(8); PG8_BAR; PG8_WAIT_L(0); PG8_MMA(0, 0, At, B0); PG8_BAR; PG8_SCHED;
;     ...
;                 for (int i = 0; i < 8; ++i) q4[i] = *(const f32x4*)(E.ssq_in + (size_t)(row0 + (i >> 2) * HALF + (i & 3) * 16) * 4);
.Lip13l_b_in:
	s_and_b32 s101, s66, 0xc0
	s_mov_b32 s100, 1
	s_cmp_lg_u32 s101, 0
	s_cselect_b32 s101, 1, 0
	v_and_b32_e32 v248, 0xff, v154
	v_lshlrev_b32_e32 v248, 4, v248
	v_add_u32_e32 v249, 0x21000, v248
	v_lshl_add_u32 v248, s6, 12, v248
	global_load_dwordx4 v[244:247], v248, s[76:77]
	s_add_u32 s19, s8, 0xfffc0080
	s_addc_u32 s26, s9, -1
	s_add_i32 s27, 0, 0x10000
	v_add_u32_e32 v142, s27, v209
	ds_read_b128 v[130:133], v142
	ds_read_b128 v[134:137], v142 offset:1024
	ds_read_b128 v[138:141], v142 offset:2048
	ds_read_b128 v[142:145], v142 offset:3072
	s_cmp_eq_u32 s18, 12
	s_cselect_b32 s69, s0, s26
	s_cselect_b32 s68, s1, s19
	s_cselect_b32 s47, s5, s13
	s_cselect_b32 s46, s7, s11
	v_lshl_add_u64 v[206:207], s[8:9], 0, v[182:183]
	s_add_i32 m0, s85, 0xc000
	ds_read_b128 v[146:149], v214
	ds_read_b128 v[150:153], v214 offset:1024
	ds_read_b128 v[186:189], v214 offset:2048
	ds_read_b128 v[190:193], v214 offset:3072
	ds_read_b128 v[194:197], v214 offset:4096
	ds_read_b128 v[198:201], v214 offset:5120
	ds_read_b128 v[202:205], v214 offset:6144
	ds_read_b128 v[216:219], v214 offset:7168
	global_load_lds_dwordx4 v[206:207], off
	s_add_i32 m0, s85, 0xe000
	v_lshl_add_u64 v[206:207], s[8:9], 0, v[184:185]
	global_load_lds_dwordx4 v[206:207], off
	s_waitcnt lgkmcnt(8)
	s_barrier
	s_waitcnt lgkmcnt(0)
	s_cmp_lg_u32 s101, 0
	s_cbranch_scc1 .Lip13l_b_0
	v_mfma_f32_16x16x32_bf16 v[126:129], v[130:133], v[146:149], 0
	v_mfma_f32_16x16x32_bf16 v[122:125], v[138:141], v[146:149], 0
	v_mfma_f32_16x16x32_bf16 v[114:117], v[130:133], v[186:189], 0
	v_mfma_f32_16x16x32_bf16 v[106:109], v[138:141], v[186:189], 0
	v_mfma_f32_16x16x32_bf16 v[94:97], v[130:133], v[194:197], 0
	v_mfma_f32_16x16x32_bf16 v[90:93], v[138:141], v[194:197], 0
	v_mfma_f32_16x16x32_bf16 v[82:85], v[130:133], v[202:205], 0
	v_mfma_f32_16x16x32_bf16 v[74:77], v[138:141], v[202:205], 0
	v_mfma_f32_16x16x32_bf16 v[126:129], v[134:137], v[150:153], v[126:129]
	v_mfma_f32_16x16x32_bf16 v[122:125], v[142:145], v[150:153], v[122:125]
	v_mfma_f32_16x16x32_bf16 v[114:117], v[134:137], v[190:193], v[114:117]
	v_mfma_f32_16x16x32_bf16 v[106:109], v[142:145], v[190:193], v[106:109]
	v_mfma_f32_16x16x32_bf16 v[94:97], v[134:137], v[198:201], v[94:97]
	v_mfma_f32_16x16x32_bf16 v[90:93], v[142:145], v[198:201], v[90:93]
	v_mfma_f32_16x16x32_bf16 v[82:85], v[134:137], v[216:219], v[82:85]
	v_mfma_f32_16x16x32_bf16 v[74:77], v[142:145], v[216:219], v[74:77]

; #define PG8_STAGE(bufoff, gbase, voff) do { _Pragma("unroll") for (int _i = 0; _i < 2; ++_i) \
;         __builtin_amdgcn_global_load_lds((const unsigned*)((const char*)(gbase) + (voff)[_i]), (LAS unsigned*)(lds + (bufoff) + ldsw + _i * 8192), 16, 0, 0); } while (0)
; #define PG8_MMA(ai, bj, At, Bt) do { __builtin_amdgcn_s_setprio(1); _Pragma("unroll") for (int m = 0; m < 4; ++m) _Pragma("unroll") for (int n = 0; n < 2; ++n) _Pragma("unroll") for (int k = 0; k < 2; ++k) \
;         acc[ai][bj][m][n] = __builtin_amdgcn_mfma_f32_16x16x32_bf16(Bt[n][k], At[m][k], acc[ai][bj][m][n], 0, 0, 0); __builtin_amdgcn_s_setprio(0); } while (0)
; #define PG8_WAIT_V(n) asm volatile("s_waitcnt vmcnt(" #n ")" ::: "memory")
; #define PG8_BAR __builtin_amdgcn_s_barrier()
; template <class Epi>
; DEVI void gemm_phase(LAS unsigned char* lds, const Gemm g, const Epi& E) {
;     ...
;             PG8_STAGE(PG8_SB(0, 1), b2 + hstepB, voffB);
;             PG8_WAIT_V(6); PG8_BAR; PG8_MMA(1, 1, At, B1); PG8_BAR;
;     ...
;                 for (int i = 0; i < 8; ++i) q4[i] = *(const f32x4*)(E.ssq_in + (size_t)(row0 + (i >> 2) * HALF + (i & 3) * 16) * 4);
.Lip13l_b_2:
	s_barrier
	s_add_u32 s26, s46, 0x40000
	s_addc_u32 s27, s47, 0
	s_add_i32 s19, s19, s84
	s_mov_b32 m0, s19
	v_lshl_add_u64 v[130:131], s[26:27], 0, v[8:9]
	global_load_lds_dwordx4 v[130:131], off
	s_add_i32 m0, s19, 0x2000
	v_lshl_add_u64 v[130:131], s[26:27], 0, v[180:181]
	global_load_lds_dwordx4 v[130:131], off
	s_waitcnt vmcnt(6)
	ds_write_b128 v249, v[244:247]
	s_barrier
	s_cmp_lg_u32 s100, 0
	s_cbranch_scc1 .Lip13l_b_3
	v_mfma_f32_16x16x32_bf16 v[50:53], v[220:223], v[146:149], 0
	v_mfma_f32_16x16x32_bf16 v[54:57], v[228:231], v[146:149], 0
	v_mfma_f32_16x16x32_bf16 v[34:37], v[220:223], v[186:189], 0
	v_mfma_f32_16x16x32_bf16 v[38:41], v[228:231], v[186:189], 0
	v_mfma_f32_16x16x32_bf16 v[18:21], v[220:223], v[194:197], 0
	v_mfma_f32_16x16x32_bf16 v[22:25], v[228:231], v[194:197], 0
	v_mfma_f32_16x16x32_bf16 v[0:3], v[220:223], v[202:205], 0
	v_mfma_f32_16x16x32_bf16 v[4:7], v[228:231], v[202:205], 0
	v_mfma_f32_16x16x32_bf16 v[50:53], v[224:227], v[150:153], v[50:53]
	v_mfma_f32_16x16x32_bf16 v[54:57], v[232:235], v[150:153], v[54:57]
	v_mfma_f32_16x16x32_bf16 v[34:37], v[224:227], v[190:193], v[34:37]
	v_mfma_f32_16x16x32_bf16 v[38:41], v[232:235], v[190:193], v[38:41]
	v_mfma_f32_16x16x32_bf16 v[18:21], v[224:227], v[198:201], v[18:21]
	v_mfma_f32_16x16x32_bf16 v[22:25], v[232:235], v[198:201], v[22:25]
	v_mfma_f32_16x16x32_bf16 v[0:3], v[224:227], v[216:219], v[0:3]
	v_mfma_f32_16x16x32_bf16 v[4:7], v[232:235], v[216:219], v[4:7]

; template <class Epi>
; DEVI void gemm_phase(LAS unsigned char* lds, const Gemm g, const Epi& E) {
;     ...
;             const int row0 = cur.pm * BM + wr * 64 + fr, col0 = cur.pn * BM + wc * 32 + (Epi::PERM ? 8 : 4) * fq; constexpr int NST = Epi::PERM ? 4 : 16;
;             float rsv[8];
;             if constexpr (Epi::RS) { f32x4 q4[8];
; #pragma unroll
;                 for (int i = 0; i < 8; ++i) q4[i] = *(const f32x4*)(E.ssq_in + (size_t)(row0 + (i >> 2) * HALF + (i & 3) * 16) * 4);
; #pragma unroll
;                 for (int i = 0; i < 8; ++i) rsv[i] = rsqrtf((((q4[i][0] + q4[i][1]) + q4[i][2]) + q4[i][3]) * (1.f / DM) + 1e-6f); }
.Lip13l_b_out:
	v_lshlrev_b32_e32 v255, 4, v208
	v_add_u32_e32 v255, 0x21000, v255
	s_setprio 0
	v_lshl_add_u32 v202, s6, 8, v208
	v_ashrrev_i32_e32 v203, 31, v202
	v_or_b32_e32 v200, 16, v202
	v_lshl_add_u64 v[130:131], v[202:203], 4, s[76:77]
	v_ashrrev_i32_e32 v201, 31, v200
	v_lshl_add_u64 v[132:133], v[200:201], 4, s[76:77]
	ds_read_b128 v[204:207], v255
	ds_read_b128 v[216:219], v255 offset:256
	v_or_b32_e32 v198, 32, v202
	v_ashrrev_i32_e32 v199, 31, v198
	v_or_b32_e32 v196, 48, v202
	v_add_u32_e32 v194, 0x80, v202
	v_lshl_add_u64 v[130:131], v[198:199], 4, s[76:77]
	v_ashrrev_i32_e32 v197, 31, v196
	v_ashrrev_i32_e32 v195, 31, v194
	v_add_u32_e32 v192, 0x90, v202
	v_add_u32_e32 v190, 0xa0, v202
	v_add_u32_e32 v188, 0xb0, v202
	v_lshl_add_u64 v[132:133], v[196:197], 4, s[76:77]
	ds_read_b128 v[146:149], v255 offset:512
	ds_read_b128 v[150:153], v255 offset:768
	v_lshl_add_u64 v[130:131], v[194:195], 4, s[76:77]
	v_ashrrev_i32_e32 v193, 31, v192
	v_ashrrev_i32_e32 v191, 31, v190
	v_ashrrev_i32_e32 v189, 31, v188
	v_lshl_add_u64 v[132:133], v[192:193], 4, s[76:77]
	ds_read_b128 v[138:141], v255 offset:2048
	ds_read_b128 v[142:145], v255 offset:2304
	v_lshl_add_u64 v[130:131], v[190:191], 4, s[76:77]
	v_lshl_add_u64 v[134:135], v[188:189], 4, s[76:77]
	ds_read_b128 v[130:133], v255 offset:2560
	s_nop 0
	ds_read_b128 v[134:137], v255 offset:2816
	s_waitcnt lgkmcnt(0)
	v_mov_b32_e32 v187, v204
	v_mov_b32_e32 v186, v216
	v_mov_b32_e32 v204, v217
	v_mov_b32_e32 v221, v206
	v_mov_b32_e32 v220, v218
	v_pk_add_f32 v[186:187], v[186:187], v[204:205]
	v_mov_b32_e32 v206, v219
	v_pk_add_f32 v[186:187], v[220:221], v[186:187]
	s_nop 0
	v_pk_add_f32 v[186:187], v[206:207], v[186:187]
	s_nop 0
	v_pk_fma_f32 v[204:205], v[186:187], s[72:73], v[160:161] op_sel_hi:[1,0,0]
	v_lshl_or_b32 v186, s4, 8, v213
	v_mul_f32_e32 v162, 0x4b800000, v205
	v_cmp_gt_f32_e32 vcc, s94, v205
	v_cmp_gt_f32_e64 s[6:7], s94, v204
	s_nop 0
	v_cndmask_b32_e32 v162, v205, v162, vcc
	v_rsq_f32_e32 v162, v162
	s_nop 0
	v_mul_f32_e32 v163, 0x45800000, v162
	v_cndmask_b32_e32 v206, v162, v163, vcc
	v_pk_mul_f32 v[128:129], v[128:129], v[206:207] op_sel_hi:[1,0]
	v_pk_mul_f32 v[126:127], v[126:127], v[206:207] op_sel_hi:[1,0]
	v_pk_mul_f32 v[124:125], v[124:125], v[206:207] op_sel_hi:[1,0]
	v_pk_mul_f32 v[122:123], v[122:123], v[206:207] op_sel_hi:[1,0]
	v_cmp_lt_i32_e32 vcc, s52, v186
	s_and_saveexec_b64 s[0:1], vcc
	s_xor_b64 s[8:9], exec, s[0:1]
	s_cbranch_execz .LBB0_361
	v_cmp_eq_u32_e64 s[4:5], s53, v186
	s_and_saveexec_b64 s[46:47], s[4:5]
	s_cbranch_execz .LBB0_360
	v_lshlrev_b64 v[216:217], 6, v[202:203]
	v_lshl_add_u64 v[216:217], s[58:59], 0, v[216:217]
	global_store_dwordx4 v[216:217], v[126:129], off
	global_store_dwordx4 v[216:217], v[122:125], off offset:16
